# baseline (speedup 1.0000x reference)
.LBB0_260:
	s_andn2_b64 vcc, exec, s[46:47]
	s_cbranch_vccnz .LBB0_254
	v_subrev_u32_e32 v254, s22, v130
	s_add_u32 s46, s22, 0x800
	s_addc_u32 s47, s23, 0
	global_load_dwordx2 v[132:133], v254, s[46:47] offset:-2048
	global_load_dwordx2 v[134:135], v254, s[46:47] offset:2048
	global_load_dwordx2 v[136:137], v254, s[46:47] offset:-2016
	global_load_dwordx2 v[138:139], v254, s[46:47] offset:2080
	global_load_dwordx2 v[140:141], v254, s[46:47] offset:-1792
	global_load_dwordx2 v[142:143], v254, s[46:47] offset:2304
	global_load_dwordx2 v[144:145], v254, s[46:47] offset:-1760
	global_load_dwordx2 v[146:147], v254, s[46:47] offset:2336
	s_add_u32 s46, s22, 0x6c800
	s_addc_u32 s47, s23, 0
	global_load_dwordx2 v[148:149], v254, s[46:47] offset:-2048
	global_load_dwordx2 v[150:151], v254, s[46:47] offset:2048
	global_load_dwordx2 v[152:153], v254, s[46:47] offset:-2016
	global_load_dwordx2 v[154:155], v254, s[46:47] offset:2080
	global_load_dwordx2 v[156:157], v254, s[46:47] offset:-1792
	global_load_dwordx2 v[158:159], v254, s[46:47] offset:2304
	global_load_dwordx2 v[160:161], v254, s[46:47] offset:-1760
	global_load_dwordx2 v[162:163], v254, s[46:47] offset:2336
	s_add_u32 s46, s22, 0xd8800
	s_addc_u32 s47, s23, 0
	global_load_dwordx2 v[164:165], v254, s[46:47] offset:-2048
	global_load_dwordx2 v[166:167], v254, s[46:47] offset:2048
	global_load_dwordx2 v[168:169], v254, s[46:47] offset:-2016
	global_load_dwordx2 v[170:171], v254, s[46:47] offset:2080
	global_load_dwordx2 v[172:173], v254, s[46:47] offset:-1792
	global_load_dwordx2 v[174:175], v254, s[46:47] offset:2304
	global_load_dwordx2 v[176:177], v254, s[46:47] offset:-1760
	global_load_dwordx2 v[178:179], v254, s[46:47] offset:2336
	s_add_u32 s46, s22, 0x144800
	s_addc_u32 s47, s23, 0
	global_load_dwordx2 v[180:181], v254, s[46:47] offset:-2048
	global_load_dwordx2 v[182:183], v254, s[46:47] offset:2048
	global_load_dwordx2 v[184:185], v254, s[46:47] offset:-2016
	global_load_dwordx2 v[186:187], v254, s[46:47] offset:2080
	global_load_dwordx2 v[188:189], v254, s[46:47] offset:-1792
	global_load_dwordx2 v[198:199], v254, s[46:47] offset:2304
	global_load_dwordx2 v[200:201], v254, s[46:47] offset:-1760
	global_load_dwordx2 v[202:203], v254, s[46:47] offset:2336
	s_waitcnt vmcnt(30)
	v_lshlrev_b32_e32 v248, 16, v134
	v_and_b32_e32 v134, 0xffff0000, v134
	v_lshlrev_b32_e32 v249, 16, v135
	v_and_b32_e32 v135, 0xffff0000, v135
	v_max_f32_e32 v248, 0xda24260, v248
	v_max_f32_e32 v134, 0xda24260, v134
	v_max_f32_e32 v249, 0xda24260, v249
	v_max_f32_e32 v135, 0xda24260, v135
	v_rcp_f32_e32 v250, v248
	v_rcp_f32_e32 v251, v134
	v_rcp_f32_e32 v252, v249
	v_rcp_f32_e32 v253, v135
	v_fma_f32 v248, -v248, v250, 1.0
	v_fma_f32 v134, -v134, v251, 1.0
	v_fma_f32 v249, -v249, v252, 1.0
	v_fma_f32 v135, -v135, v253, 1.0
	v_fmac_f32_e32 v250, v248, v250
	v_fmac_f32_e32 v251, v134, v251
	v_fmac_f32_e32 v252, v249, v252
	v_fmac_f32_e32 v253, v135, v253
	v_lshlrev_b32_e32 v248, 16, v132
	v_and_b32_e32 v132, 0xffff0000, v132
	v_lshlrev_b32_e32 v249, 16, v133
	v_and_b32_e32 v133, 0xffff0000, v133
	v_mul_f32_e32 v250, v248, v250
	v_mul_f32_e32 v251, v132, v251
	v_mul_f32_e32 v252, v249, v252
	v_mul_f32_e32 v253, v133, v253
	v_mul_f32_e32 v126, v126, v250
	v_mul_f32_e32 v127, v127, v251
	v_mul_f32_e32 v128, v128, v252
	v_mul_f32_e32 v129, v129, v253
	s_add_u32 s46, s22, 0x360800
	s_addc_u32 s47, s23, 0
	global_load_dwordx2 v[132:133], v254, s[46:47] offset:-2048
	global_load_dwordx2 v[134:135], v254, s[46:47] offset:2048
	s_waitcnt vmcnt(30)
	v_lshlrev_b32_e32 v248, 16, v138
	v_and_b32_e32 v138, 0xffff0000, v138
	v_lshlrev_b32_e32 v249, 16, v139
	v_and_b32_e32 v139, 0xffff0000, v139
	v_max_f32_e32 v248, 0xda24260, v248
	v_max_f32_e32 v138, 0xda24260, v138
	v_max_f32_e32 v249, 0xda24260, v249
	v_max_f32_e32 v139, 0xda24260, v139
	v_rcp_f32_e32 v250, v248
	v_rcp_f32_e32 v251, v138
	v_rcp_f32_e32 v252, v249
	v_rcp_f32_e32 v253, v139
	v_fma_f32 v248, -v248, v250, 1.0
	v_fma_f32 v138, -v138, v251, 1.0
	v_fma_f32 v249, -v249, v252, 1.0
	v_fma_f32 v139, -v139, v253, 1.0
	v_fmac_f32_e32 v250, v248, v250
	v_fmac_f32_e32 v251, v138, v251
	v_fmac_f32_e32 v252, v249, v252
	v_fmac_f32_e32 v253, v139, v253
	v_lshlrev_b32_e32 v248, 16, v136
	v_and_b32_e32 v136, 0xffff0000, v136
	v_lshlrev_b32_e32 v249, 16, v137
	v_and_b32_e32 v137, 0xffff0000, v137
	v_mul_f32_e32 v250, v248, v250
	v_mul_f32_e32 v251, v136, v251
	v_mul_f32_e32 v252, v249, v252
	v_mul_f32_e32 v253, v137, v253
	v_mul_f32_e32 v122, v122, v250
	v_mul_f32_e32 v123, v123, v251
	v_mul_f32_e32 v124, v124, v252
	v_mul_f32_e32 v125, v125, v253
	global_load_dwordx2 v[136:137], v254, s[46:47] offset:-2016
	global_load_dwordx2 v[138:139], v254, s[46:47] offset:2080
	s_waitcnt vmcnt(30)
	v_lshlrev_b32_e32 v248, 16, v142
	v_and_b32_e32 v142, 0xffff0000, v142
	v_lshlrev_b32_e32 v249, 16, v143
	v_and_b32_e32 v143, 0xffff0000, v143
	v_max_f32_e32 v248, 0xda24260, v248
	v_max_f32_e32 v142, 0xda24260, v142
	v_max_f32_e32 v249, 0xda24260, v249
	v_max_f32_e32 v143, 0xda24260, v143
	v_rcp_f32_e32 v250, v248
	v_rcp_f32_e32 v251, v142
	v_rcp_f32_e32 v252, v249
	v_rcp_f32_e32 v253, v143
	v_fma_f32 v248, -v248, v250, 1.0
	v_fma_f32 v142, -v142, v251, 1.0
	v_fma_f32 v249, -v249, v252, 1.0
	v_fma_f32 v143, -v143, v253, 1.0
	v_fmac_f32_e32 v250, v248, v250
	v_fmac_f32_e32 v251, v142, v251
	v_fmac_f32_e32 v252, v249, v252
	v_fmac_f32_e32 v253, v143, v253
	v_lshlrev_b32_e32 v248, 16, v140
	v_and_b32_e32 v140, 0xffff0000, v140
	v_lshlrev_b32_e32 v249, 16, v141
	v_and_b32_e32 v141, 0xffff0000, v141
	v_mul_f32_e32 v250, v248, v250
	v_mul_f32_e32 v251, v140, v251
	v_mul_f32_e32 v252, v249, v252
	v_mul_f32_e32 v253, v141, v253
	v_mul_f32_e32 v94, v94, v250
	v_mul_f32_e32 v95, v95, v251
	v_mul_f32_e32 v96, v96, v252
	v_mul_f32_e32 v97, v97, v253
	global_load_dwordx2 v[140:141], v254, s[46:47] offset:-1792
	global_load_dwordx2 v[142:143], v254, s[46:47] offset:2304
	s_waitcnt vmcnt(30)
	v_lshlrev_b32_e32 v248, 16, v146
	v_and_b32_e32 v146, 0xffff0000, v146
	v_lshlrev_b32_e32 v249, 16, v147
	v_and_b32_e32 v147, 0xffff0000, v147
	v_max_f32_e32 v248, 0xda24260, v248
	v_max_f32_e32 v146, 0xda24260, v146
	v_max_f32_e32 v249, 0xda24260, v249
	v_max_f32_e32 v147, 0xda24260, v147
	v_rcp_f32_e32 v250, v248
	v_rcp_f32_e32 v251, v146
	v_rcp_f32_e32 v252, v249
	v_rcp_f32_e32 v253, v147
	v_fma_f32 v248, -v248, v250, 1.0
	v_fma_f32 v146, -v146, v251, 1.0
	v_fma_f32 v249, -v249, v252, 1.0
	v_fma_f32 v147, -v147, v253, 1.0
	v_fmac_f32_e32 v250, v248, v250
	v_fmac_f32_e32 v251, v146, v251
	v_fmac_f32_e32 v252, v249, v252
	v_fmac_f32_e32 v253, v147, v253
	v_lshlrev_b32_e32 v248, 16, v144
	v_and_b32_e32 v144, 0xffff0000, v144
	v_lshlrev_b32_e32 v249, 16, v145
	v_and_b32_e32 v145, 0xffff0000, v145
	v_mul_f32_e32 v250, v248, v250
	v_mul_f32_e32 v251, v144, v251
	v_mul_f32_e32 v252, v249, v252
	v_mul_f32_e32 v253, v145, v253
	v_mul_f32_e32 v90, v90, v250
	v_mul_f32_e32 v91, v91, v251
	v_mul_f32_e32 v92, v92, v252
	v_mul_f32_e32 v93, v93, v253
	global_load_dwordx2 v[144:145], v254, s[46:47] offset:-1760
	global_load_dwordx2 v[146:147], v254, s[46:47] offset:2336
	s_waitcnt vmcnt(30)
	v_lshlrev_b32_e32 v248, 16, v150
	v_and_b32_e32 v150, 0xffff0000, v150
	v_lshlrev_b32_e32 v249, 16, v151
	v_and_b32_e32 v151, 0xffff0000, v151
	v_max_f32_e32 v248, 0xda24260, v248
	v_max_f32_e32 v150, 0xda24260, v150
	v_max_f32_e32 v249, 0xda24260, v249
	v_max_f32_e32 v151, 0xda24260, v151
	v_rcp_f32_e32 v250, v248
	v_rcp_f32_e32 v251, v150
	v_rcp_f32_e32 v252, v249
	v_rcp_f32_e32 v253, v151
	v_fma_f32 v248, -v248, v250, 1.0
	v_fma_f32 v150, -v150, v251, 1.0
	v_fma_f32 v249, -v249, v252, 1.0
	v_fma_f32 v151, -v151, v253, 1.0
	v_fmac_f32_e32 v250, v248, v250
	v_fmac_f32_e32 v251, v150, v251
	v_fmac_f32_e32 v252, v249, v252
	v_fmac_f32_e32 v253, v151, v253
	v_lshlrev_b32_e32 v248, 16, v148
	v_and_b32_e32 v148, 0xffff0000, v148
	v_lshlrev_b32_e32 v249, 16, v149
	v_and_b32_e32 v149, 0xffff0000, v149
	v_mul_f32_e32 v250, v248, v250
	v_mul_f32_e32 v251, v148, v251
	v_mul_f32_e32 v252, v249, v252
	v_mul_f32_e32 v253, v149, v253
	v_mul_f32_e32 v118, v118, v250
	v_mul_f32_e32 v119, v119, v251
	v_mul_f32_e32 v120, v120, v252
	v_mul_f32_e32 v121, v121, v253
	s_add_u32 s46, s22, 0x3cc800
	s_addc_u32 s47, s23, 0
	global_load_dwordx2 v[148:149], v254, s[46:47] offset:-2048
	global_load_dwordx2 v[150:151], v254, s[46:47] offset:2048
	s_waitcnt vmcnt(30)
	v_lshlrev_b32_e32 v248, 16, v154
	v_and_b32_e32 v154, 0xffff0000, v154
	v_lshlrev_b32_e32 v249, 16, v155
	v_and_b32_e32 v155, 0xffff0000, v155
	v_max_f32_e32 v248, 0xda24260, v248
	v_max_f32_e32 v154, 0xda24260, v154
	v_max_f32_e32 v249, 0xda24260, v249
	v_max_f32_e32 v155, 0xda24260, v155
	v_rcp_f32_e32 v250, v248
	v_rcp_f32_e32 v251, v154
	v_rcp_f32_e32 v252, v249
	v_rcp_f32_e32 v253, v155
	v_fma_f32 v248, -v248, v250, 1.0
	v_fma_f32 v154, -v154, v251, 1.0
	v_fma_f32 v249, -v249, v252, 1.0
	v_fma_f32 v155, -v155, v253, 1.0
	v_fmac_f32_e32 v250, v248, v250
	v_fmac_f32_e32 v251, v154, v251
	v_fmac_f32_e32 v252, v249, v252
	v_fmac_f32_e32 v253, v155, v253
	v_lshlrev_b32_e32 v248, 16, v152
	v_and_b32_e32 v152, 0xffff0000, v152
	v_lshlrev_b32_e32 v249, 16, v153
	v_and_b32_e32 v153, 0xffff0000, v153
	v_mul_f32_e32 v250, v248, v250
	v_mul_f32_e32 v251, v152, v251
	v_mul_f32_e32 v252, v249, v252
	v_mul_f32_e32 v253, v153, v253
	v_mul_f32_e32 v114, v114, v250
	v_mul_f32_e32 v115, v115, v251
	v_mul_f32_e32 v116, v116, v252
	v_mul_f32_e32 v117, v117, v253
	global_load_dwordx2 v[152:153], v254, s[46:47] offset:-2016
	global_load_dwordx2 v[154:155], v254, s[46:47] offset:2080
	s_waitcnt vmcnt(30)
	v_lshlrev_b32_e32 v248, 16, v158
	v_and_b32_e32 v158, 0xffff0000, v158
	v_lshlrev_b32_e32 v249, 16, v159
	v_and_b32_e32 v159, 0xffff0000, v159
	v_max_f32_e32 v248, 0xda24260, v248
	v_max_f32_e32 v158, 0xda24260, v158
	v_max_f32_e32 v249, 0xda24260, v249
	v_max_f32_e32 v159, 0xda24260, v159
	v_rcp_f32_e32 v250, v248
	v_rcp_f32_e32 v251, v158
	v_rcp_f32_e32 v252, v249
	v_rcp_f32_e32 v253, v159
	v_fma_f32 v248, -v248, v250, 1.0
	v_fma_f32 v158, -v158, v251, 1.0
	v_fma_f32 v249, -v249, v252, 1.0
	v_fma_f32 v159, -v159, v253, 1.0
	v_fmac_f32_e32 v250, v248, v250
	v_fmac_f32_e32 v251, v158, v251
	v_fmac_f32_e32 v252, v249, v252
	v_fmac_f32_e32 v253, v159, v253
	v_lshlrev_b32_e32 v248, 16, v156
	v_and_b32_e32 v156, 0xffff0000, v156
	v_lshlrev_b32_e32 v249, 16, v157
	v_and_b32_e32 v157, 0xffff0000, v157
	v_mul_f32_e32 v250, v248, v250
	v_mul_f32_e32 v251, v156, v251
	v_mul_f32_e32 v252, v249, v252
	v_mul_f32_e32 v253, v157, v253
	v_mul_f32_e32 v86, v86, v250
	v_mul_f32_e32 v87, v87, v251
	v_mul_f32_e32 v88, v88, v252
	v_mul_f32_e32 v89, v89, v253
	global_load_dwordx2 v[156:157], v254, s[46:47] offset:-1792
	global_load_dwordx2 v[158:159], v254, s[46:47] offset:2304
	s_waitcnt vmcnt(30)
	v_lshlrev_b32_e32 v248, 16, v162
	v_and_b32_e32 v162, 0xffff0000, v162
	v_lshlrev_b32_e32 v249, 16, v163
	v_and_b32_e32 v163, 0xffff0000, v163
	v_max_f32_e32 v248, 0xda24260, v248
	v_max_f32_e32 v162, 0xda24260, v162
	v_max_f32_e32 v249, 0xda24260, v249
	v_max_f32_e32 v163, 0xda24260, v163
	v_rcp_f32_e32 v250, v248
	v_rcp_f32_e32 v251, v162
	v_rcp_f32_e32 v252, v249
	v_rcp_f32_e32 v253, v163
	v_fma_f32 v248, -v248, v250, 1.0
	v_fma_f32 v162, -v162, v251, 1.0
	v_fma_f32 v249, -v249, v252, 1.0
	v_fma_f32 v163, -v163, v253, 1.0
	v_fmac_f32_e32 v250, v248, v250
	v_fmac_f32_e32 v251, v162, v251
	v_fmac_f32_e32 v252, v249, v252
	v_fmac_f32_e32 v253, v163, v253
	v_lshlrev_b32_e32 v248, 16, v160
	v_and_b32_e32 v160, 0xffff0000, v160
	v_lshlrev_b32_e32 v249, 16, v161
	v_and_b32_e32 v161, 0xffff0000, v161
	v_mul_f32_e32 v250, v248, v250
	v_mul_f32_e32 v251, v160, v251
	v_mul_f32_e32 v252, v249, v252
	v_mul_f32_e32 v253, v161, v253
	v_mul_f32_e32 v82, v82, v250
	v_mul_f32_e32 v83, v83, v251
	v_mul_f32_e32 v84, v84, v252
	v_mul_f32_e32 v85, v85, v253
	global_load_dwordx2 v[160:161], v254, s[46:47] offset:-1760
	global_load_dwordx2 v[162:163], v254, s[46:47] offset:2336
	s_waitcnt vmcnt(30)
	v_lshlrev_b32_e32 v248, 16, v166
	v_and_b32_e32 v166, 0xffff0000, v166
	v_lshlrev_b32_e32 v249, 16, v167
	v_and_b32_e32 v167, 0xffff0000, v167
	v_max_f32_e32 v248, 0xda24260, v248
	v_max_f32_e32 v166, 0xda24260, v166
	v_max_f32_e32 v249, 0xda24260, v249
	v_max_f32_e32 v167, 0xda24260, v167
	v_rcp_f32_e32 v250, v248
	v_rcp_f32_e32 v251, v166
	v_rcp_f32_e32 v252, v249
	v_rcp_f32_e32 v253, v167
	v_fma_f32 v248, -v248, v250, 1.0
	v_fma_f32 v166, -v166, v251, 1.0
	v_fma_f32 v249, -v249, v252, 1.0
	v_fma_f32 v167, -v167, v253, 1.0
	v_fmac_f32_e32 v250, v248, v250
	v_fmac_f32_e32 v251, v166, v251
	v_fmac_f32_e32 v252, v249, v252
	v_fmac_f32_e32 v253, v167, v253
	v_lshlrev_b32_e32 v248, 16, v164
	v_and_b32_e32 v164, 0xffff0000, v164
	v_lshlrev_b32_e32 v249, 16, v165
	v_and_b32_e32 v165, 0xffff0000, v165
	v_mul_f32_e32 v250, v248, v250
	v_mul_f32_e32 v251, v164, v251
	v_mul_f32_e32 v252, v249, v252
	v_mul_f32_e32 v253, v165, v253
	v_mul_f32_e32 v110, v110, v250
	v_mul_f32_e32 v111, v111, v251
	v_mul_f32_e32 v112, v112, v252
	v_mul_f32_e32 v113, v113, v253
	s_add_u32 s46, s22, 0x438800
	s_addc_u32 s47, s23, 0
	global_load_dwordx2 v[164:165], v254, s[46:47] offset:-2048
	global_load_dwordx2 v[166:167], v254, s[46:47] offset:2048
	s_waitcnt vmcnt(30)
	v_lshlrev_b32_e32 v248, 16, v170
	v_and_b32_e32 v170, 0xffff0000, v170
	v_lshlrev_b32_e32 v249, 16, v171
	v_and_b32_e32 v171, 0xffff0000, v171
	v_max_f32_e32 v248, 0xda24260, v248
	v_max_f32_e32 v170, 0xda24260, v170
	v_max_f32_e32 v249, 0xda24260, v249
	v_max_f32_e32 v171, 0xda24260, v171
	v_rcp_f32_e32 v250, v248
	v_rcp_f32_e32 v251, v170
	v_rcp_f32_e32 v252, v249
	v_rcp_f32_e32 v253, v171
	v_fma_f32 v248, -v248, v250, 1.0
	v_fma_f32 v170, -v170, v251, 1.0
	v_fma_f32 v249, -v249, v252, 1.0
	v_fma_f32 v171, -v171, v253, 1.0
	v_fmac_f32_e32 v250, v248, v250
	v_fmac_f32_e32 v251, v170, v251
	v_fmac_f32_e32 v252, v249, v252
	v_fmac_f32_e32 v253, v171, v253
	v_lshlrev_b32_e32 v248, 16, v168
	v_and_b32_e32 v168, 0xffff0000, v168
	v_lshlrev_b32_e32 v249, 16, v169
	v_and_b32_e32 v169, 0xffff0000, v169
	v_mul_f32_e32 v250, v248, v250
	v_mul_f32_e32 v251, v168, v251
	v_mul_f32_e32 v252, v249, v252
	v_mul_f32_e32 v253, v169, v253
	v_mul_f32_e32 v106, v106, v250
	v_mul_f32_e32 v107, v107, v251
	v_mul_f32_e32 v108, v108, v252
	v_mul_f32_e32 v109, v109, v253
	global_load_dwordx2 v[168:169], v254, s[46:47] offset:-2016
	global_load_dwordx2 v[170:171], v254, s[46:47] offset:2080
	s_waitcnt vmcnt(30)
	v_lshlrev_b32_e32 v248, 16, v174
	v_and_b32_e32 v174, 0xffff0000, v174
	v_lshlrev_b32_e32 v249, 16, v175
	v_and_b32_e32 v175, 0xffff0000, v175
	v_max_f32_e32 v248, 0xda24260, v248
	v_max_f32_e32 v174, 0xda24260, v174
	v_max_f32_e32 v249, 0xda24260, v249
	v_max_f32_e32 v175, 0xda24260, v175
	v_rcp_f32_e32 v250, v248
	v_rcp_f32_e32 v251, v174
	v_rcp_f32_e32 v252, v249
	v_rcp_f32_e32 v253, v175
	v_fma_f32 v248, -v248, v250, 1.0
	v_fma_f32 v174, -v174, v251, 1.0
	v_fma_f32 v249, -v249, v252, 1.0
	v_fma_f32 v175, -v175, v253, 1.0
	v_fmac_f32_e32 v250, v248, v250
	v_fmac_f32_e32 v251, v174, v251
	v_fmac_f32_e32 v252, v249, v252
	v_fmac_f32_e32 v253, v175, v253
	v_lshlrev_b32_e32 v248, 16, v172
	v_and_b32_e32 v172, 0xffff0000, v172
	v_lshlrev_b32_e32 v249, 16, v173
	v_and_b32_e32 v173, 0xffff0000, v173
	v_mul_f32_e32 v250, v248, v250
	v_mul_f32_e32 v251, v172, v251
	v_mul_f32_e32 v252, v249, v252
	v_mul_f32_e32 v253, v173, v253
	v_mul_f32_e32 v78, v78, v250
	v_mul_f32_e32 v79, v79, v251
	v_mul_f32_e32 v80, v80, v252
	v_mul_f32_e32 v81, v81, v253
	global_load_dwordx2 v[172:173], v254, s[46:47] offset:-1792
	global_load_dwordx2 v[174:175], v254, s[46:47] offset:2304
	s_waitcnt vmcnt(30)
	v_lshlrev_b32_e32 v248, 16, v178
	v_and_b32_e32 v178, 0xffff0000, v178
	v_lshlrev_b32_e32 v249, 16, v179
	v_and_b32_e32 v179, 0xffff0000, v179
	v_max_f32_e32 v248, 0xda24260, v248
	v_max_f32_e32 v178, 0xda24260, v178
	v_max_f32_e32 v249, 0xda24260, v249
	v_max_f32_e32 v179, 0xda24260, v179
	v_rcp_f32_e32 v250, v248
	v_rcp_f32_e32 v251, v178
	v_rcp_f32_e32 v252, v249
	v_rcp_f32_e32 v253, v179
	v_fma_f32 v248, -v248, v250, 1.0
	v_fma_f32 v178, -v178, v251, 1.0
	v_fma_f32 v249, -v249, v252, 1.0
	v_fma_f32 v179, -v179, v253, 1.0
	v_fmac_f32_e32 v250, v248, v250
	v_fmac_f32_e32 v251, v178, v251
	v_fmac_f32_e32 v252, v249, v252
	v_fmac_f32_e32 v253, v179, v253
	v_lshlrev_b32_e32 v248, 16, v176
	v_and_b32_e32 v176, 0xffff0000, v176
	v_lshlrev_b32_e32 v249, 16, v177
	v_and_b32_e32 v177, 0xffff0000, v177
	v_mul_f32_e32 v250, v248, v250
	v_mul_f32_e32 v251, v176, v251
	v_mul_f32_e32 v252, v249, v252
	v_mul_f32_e32 v253, v177, v253
	v_mul_f32_e32 v74, v74, v250
	v_mul_f32_e32 v75, v75, v251
	v_mul_f32_e32 v76, v76, v252
	v_mul_f32_e32 v77, v77, v253
	global_load_dwordx2 v[176:177], v254, s[46:47] offset:-1760
	global_load_dwordx2 v[178:179], v254, s[46:47] offset:2336
	s_waitcnt vmcnt(30)
	v_lshlrev_b32_e32 v248, 16, v182
	v_and_b32_e32 v182, 0xffff0000, v182
	v_lshlrev_b32_e32 v249, 16, v183
	v_and_b32_e32 v183, 0xffff0000, v183
	v_max_f32_e32 v248, 0xda24260, v248
	v_max_f32_e32 v182, 0xda24260, v182
	v_max_f32_e32 v249, 0xda24260, v249
	v_max_f32_e32 v183, 0xda24260, v183
	v_rcp_f32_e32 v250, v248
	v_rcp_f32_e32 v251, v182
	v_rcp_f32_e32 v252, v249
	v_rcp_f32_e32 v253, v183
	v_fma_f32 v248, -v248, v250, 1.0
	v_fma_f32 v182, -v182, v251, 1.0
	v_fma_f32 v249, -v249, v252, 1.0
	v_fma_f32 v183, -v183, v253, 1.0
	v_fmac_f32_e32 v250, v248, v250
	v_fmac_f32_e32 v251, v182, v251
	v_fmac_f32_e32 v252, v249, v252
	v_fmac_f32_e32 v253, v183, v253
	v_lshlrev_b32_e32 v248, 16, v180
	v_and_b32_e32 v180, 0xffff0000, v180
	v_lshlrev_b32_e32 v249, 16, v181
	v_and_b32_e32 v181, 0xffff0000, v181
	v_mul_f32_e32 v250, v248, v250
	v_mul_f32_e32 v251, v180, v251
	v_mul_f32_e32 v252, v249, v252
	v_mul_f32_e32 v253, v181, v253
	v_mul_f32_e32 v102, v102, v250
	v_mul_f32_e32 v103, v103, v251
	v_mul_f32_e32 v104, v104, v252
	v_mul_f32_e32 v105, v105, v253
	s_add_u32 s46, s22, 0x4a4800
	s_addc_u32 s47, s23, 0
	global_load_dwordx2 v[180:181], v254, s[46:47] offset:-2048
	global_load_dwordx2 v[182:183], v254, s[46:47] offset:2048
	s_waitcnt vmcnt(30)
	v_lshlrev_b32_e32 v248, 16, v186
	v_and_b32_e32 v186, 0xffff0000, v186
	v_lshlrev_b32_e32 v249, 16, v187
	v_and_b32_e32 v187, 0xffff0000, v187
	v_max_f32_e32 v248, 0xda24260, v248
	v_max_f32_e32 v186, 0xda24260, v186
	v_max_f32_e32 v249, 0xda24260, v249
	v_max_f32_e32 v187, 0xda24260, v187
	v_rcp_f32_e32 v250, v248
	v_rcp_f32_e32 v251, v186
	v_rcp_f32_e32 v252, v249
	v_rcp_f32_e32 v253, v187
	v_fma_f32 v248, -v248, v250, 1.0
	v_fma_f32 v186, -v186, v251, 1.0
	v_fma_f32 v249, -v249, v252, 1.0
	v_fma_f32 v187, -v187, v253, 1.0
	v_fmac_f32_e32 v250, v248, v250
	v_fmac_f32_e32 v251, v186, v251
	v_fmac_f32_e32 v252, v249, v252
	v_fmac_f32_e32 v253, v187, v253
	v_lshlrev_b32_e32 v248, 16, v184
	v_and_b32_e32 v184, 0xffff0000, v184
	v_lshlrev_b32_e32 v249, 16, v185
	v_and_b32_e32 v185, 0xffff0000, v185
	v_mul_f32_e32 v250, v248, v250
	v_mul_f32_e32 v251, v184, v251
	v_mul_f32_e32 v252, v249, v252
	v_mul_f32_e32 v253, v185, v253
	v_mul_f32_e32 v98, v98, v250
	v_mul_f32_e32 v99, v99, v251
	v_mul_f32_e32 v100, v100, v252
	v_mul_f32_e32 v101, v101, v253
	global_load_dwordx2 v[184:185], v254, s[46:47] offset:-2016
	global_load_dwordx2 v[186:187], v254, s[46:47] offset:2080
	s_waitcnt vmcnt(30)
	v_lshlrev_b32_e32 v248, 16, v198
	v_and_b32_e32 v198, 0xffff0000, v198
	v_lshlrev_b32_e32 v249, 16, v199
	v_and_b32_e32 v199, 0xffff0000, v199
	v_max_f32_e32 v248, 0xda24260, v248
	v_max_f32_e32 v198, 0xda24260, v198
	v_max_f32_e32 v249, 0xda24260, v249
	v_max_f32_e32 v199, 0xda24260, v199
	v_rcp_f32_e32 v250, v248
	v_rcp_f32_e32 v251, v198
	v_rcp_f32_e32 v252, v249
	v_rcp_f32_e32 v253, v199
	v_fma_f32 v248, -v248, v250, 1.0
	v_fma_f32 v198, -v198, v251, 1.0
	v_fma_f32 v249, -v249, v252, 1.0
	v_fma_f32 v199, -v199, v253, 1.0
	v_fmac_f32_e32 v250, v248, v250
	v_fmac_f32_e32 v251, v198, v251
	v_fmac_f32_e32 v252, v249, v252
	v_fmac_f32_e32 v253, v199, v253
	v_lshlrev_b32_e32 v248, 16, v188
	v_and_b32_e32 v188, 0xffff0000, v188
	v_lshlrev_b32_e32 v249, 16, v189
	v_and_b32_e32 v189, 0xffff0000, v189
	v_mul_f32_e32 v250, v248, v250
	v_mul_f32_e32 v251, v188, v251
	v_mul_f32_e32 v252, v249, v252
	v_mul_f32_e32 v253, v189, v253
	v_mul_f32_e32 v70, v70, v250
	v_mul_f32_e32 v71, v71, v251
	v_mul_f32_e32 v72, v72, v252
	v_mul_f32_e32 v73, v73, v253
	global_load_dwordx2 v[188:189], v254, s[46:47] offset:-1792
	global_load_dwordx2 v[198:199], v254, s[46:47] offset:2304
	s_waitcnt vmcnt(30)
	v_lshlrev_b32_e32 v248, 16, v202
	v_and_b32_e32 v202, 0xffff0000, v202
	v_lshlrev_b32_e32 v249, 16, v203
	v_and_b32_e32 v203, 0xffff0000, v203
	v_max_f32_e32 v248, 0xda24260, v248
	v_max_f32_e32 v202, 0xda24260, v202
	v_max_f32_e32 v249, 0xda24260, v249
	v_max_f32_e32 v203, 0xda24260, v203
	v_rcp_f32_e32 v250, v248
	v_rcp_f32_e32 v251, v202
	v_rcp_f32_e32 v252, v249
	v_rcp_f32_e32 v253, v203
	v_fma_f32 v248, -v248, v250, 1.0
	v_fma_f32 v202, -v202, v251, 1.0
	v_fma_f32 v249, -v249, v252, 1.0
	v_fma_f32 v203, -v203, v253, 1.0
	v_fmac_f32_e32 v250, v248, v250
	v_fmac_f32_e32 v251, v202, v251
	v_fmac_f32_e32 v252, v249, v252
	v_fmac_f32_e32 v253, v203, v253
	v_lshlrev_b32_e32 v248, 16, v200
	v_and_b32_e32 v200, 0xffff0000, v200
	v_lshlrev_b32_e32 v249, 16, v201
	v_and_b32_e32 v201, 0xffff0000, v201
	v_mul_f32_e32 v250, v248, v250
	v_mul_f32_e32 v251, v200, v251
	v_mul_f32_e32 v252, v249, v252
	v_mul_f32_e32 v253, v201, v253
	v_mul_f32_e32 v66, v66, v250
	v_mul_f32_e32 v67, v67, v251
	v_mul_f32_e32 v68, v68, v252
	v_mul_f32_e32 v69, v69, v253
	global_load_dwordx2 v[200:201], v254, s[46:47] offset:-1760
	global_load_dwordx2 v[202:203], v254, s[46:47] offset:2336
	s_waitcnt vmcnt(30)
	v_lshlrev_b32_e32 v248, 16, v134
	v_and_b32_e32 v134, 0xffff0000, v134
	v_lshlrev_b32_e32 v249, 16, v135
	v_and_b32_e32 v135, 0xffff0000, v135
	v_max_f32_e32 v248, 0xda24260, v248
	v_max_f32_e32 v134, 0xda24260, v134
	v_max_f32_e32 v249, 0xda24260, v249
	v_max_f32_e32 v135, 0xda24260, v135
	v_rcp_f32_e32 v250, v248
	v_rcp_f32_e32 v251, v134
	v_rcp_f32_e32 v252, v249
	v_rcp_f32_e32 v253, v135
	v_fma_f32 v248, -v248, v250, 1.0
	v_fma_f32 v134, -v134, v251, 1.0
	v_fma_f32 v249, -v249, v252, 1.0
	v_fma_f32 v135, -v135, v253, 1.0
	v_fmac_f32_e32 v250, v248, v250
	v_fmac_f32_e32 v251, v134, v251
	v_fmac_f32_e32 v252, v249, v252
	v_fmac_f32_e32 v253, v135, v253
	v_lshlrev_b32_e32 v248, 16, v132
	v_and_b32_e32 v132, 0xffff0000, v132
	v_lshlrev_b32_e32 v249, 16, v133
	v_and_b32_e32 v133, 0xffff0000, v133
	v_mul_f32_e32 v250, v248, v250
	v_mul_f32_e32 v251, v132, v251
	v_mul_f32_e32 v252, v249, v252
	v_mul_f32_e32 v253, v133, v253
	v_mul_f32_e32 v62, v62, v250
	v_mul_f32_e32 v63, v63, v251
	v_mul_f32_e32 v64, v64, v252
	v_mul_f32_e32 v65, v65, v253
	s_waitcnt vmcnt(28)
	v_lshlrev_b32_e32 v248, 16, v138
	v_and_b32_e32 v138, 0xffff0000, v138
	v_lshlrev_b32_e32 v249, 16, v139
	v_and_b32_e32 v139, 0xffff0000, v139
	v_max_f32_e32 v248, 0xda24260, v248
	v_max_f32_e32 v138, 0xda24260, v138
	v_max_f32_e32 v249, 0xda24260, v249
	v_max_f32_e32 v139, 0xda24260, v139
	v_rcp_f32_e32 v250, v248
	v_rcp_f32_e32 v251, v138
	v_rcp_f32_e32 v252, v249
	v_rcp_f32_e32 v253, v139
	v_fma_f32 v248, -v248, v250, 1.0
	v_fma_f32 v138, -v138, v251, 1.0
	v_fma_f32 v249, -v249, v252, 1.0
	v_fma_f32 v139, -v139, v253, 1.0
	v_fmac_f32_e32 v250, v248, v250
	v_fmac_f32_e32 v251, v138, v251
	v_fmac_f32_e32 v252, v249, v252
	v_fmac_f32_e32 v253, v139, v253
	v_lshlrev_b32_e32 v248, 16, v136
	v_and_b32_e32 v136, 0xffff0000, v136
	v_lshlrev_b32_e32 v249, 16, v137
	v_and_b32_e32 v137, 0xffff0000, v137
	v_mul_f32_e32 v250, v248, v250
	v_mul_f32_e32 v251, v136, v251
	v_mul_f32_e32 v252, v249, v252
	v_mul_f32_e32 v253, v137, v253
	v_mul_f32_e32 v58, v58, v250
	v_mul_f32_e32 v59, v59, v251
	v_mul_f32_e32 v60, v60, v252
	v_mul_f32_e32 v61, v61, v253
	s_waitcnt vmcnt(26)
	v_lshlrev_b32_e32 v248, 16, v142
	v_and_b32_e32 v142, 0xffff0000, v142
	v_lshlrev_b32_e32 v249, 16, v143
	v_and_b32_e32 v143, 0xffff0000, v143
	v_max_f32_e32 v248, 0xda24260, v248
	v_max_f32_e32 v142, 0xda24260, v142
	v_max_f32_e32 v249, 0xda24260, v249
	v_max_f32_e32 v143, 0xda24260, v143
	v_rcp_f32_e32 v250, v248
	v_rcp_f32_e32 v251, v142
	v_rcp_f32_e32 v252, v249
	v_rcp_f32_e32 v253, v143
	v_fma_f32 v248, -v248, v250, 1.0
	v_fma_f32 v142, -v142, v251, 1.0
	v_fma_f32 v249, -v249, v252, 1.0
	v_fma_f32 v143, -v143, v253, 1.0
	v_fmac_f32_e32 v250, v248, v250
	v_fmac_f32_e32 v251, v142, v251
	v_fmac_f32_e32 v252, v249, v252
	v_fmac_f32_e32 v253, v143, v253
	v_lshlrev_b32_e32 v248, 16, v140
	v_and_b32_e32 v140, 0xffff0000, v140
	v_lshlrev_b32_e32 v249, 16, v141
	v_and_b32_e32 v141, 0xffff0000, v141
	v_mul_f32_e32 v250, v248, v250
	v_mul_f32_e32 v251, v140, v251
	v_mul_f32_e32 v252, v249, v252
	v_mul_f32_e32 v253, v141, v253
	v_mul_f32_e32 v30, v30, v250
	v_mul_f32_e32 v31, v31, v251
	v_mul_f32_e32 v32, v32, v252
	v_mul_f32_e32 v33, v33, v253
	s_waitcnt vmcnt(24)
	v_lshlrev_b32_e32 v248, 16, v146
	v_and_b32_e32 v146, 0xffff0000, v146
	v_lshlrev_b32_e32 v249, 16, v147
	v_and_b32_e32 v147, 0xffff0000, v147
	v_max_f32_e32 v248, 0xda24260, v248
	v_max_f32_e32 v146, 0xda24260, v146
	v_max_f32_e32 v249, 0xda24260, v249
	v_max_f32_e32 v147, 0xda24260, v147
	v_rcp_f32_e32 v250, v248
	v_rcp_f32_e32 v251, v146
	v_rcp_f32_e32 v252, v249
	v_rcp_f32_e32 v253, v147
	v_fma_f32 v248, -v248, v250, 1.0
	v_fma_f32 v146, -v146, v251, 1.0
	v_fma_f32 v249, -v249, v252, 1.0
	v_fma_f32 v147, -v147, v253, 1.0
	v_fmac_f32_e32 v250, v248, v250
	v_fmac_f32_e32 v251, v146, v251
	v_fmac_f32_e32 v252, v249, v252
	v_fmac_f32_e32 v253, v147, v253
	v_lshlrev_b32_e32 v248, 16, v144
	v_and_b32_e32 v144, 0xffff0000, v144
	v_lshlrev_b32_e32 v249, 16, v145
	v_and_b32_e32 v145, 0xffff0000, v145
	v_mul_f32_e32 v250, v248, v250
	v_mul_f32_e32 v251, v144, v251
	v_mul_f32_e32 v252, v249, v252
	v_mul_f32_e32 v253, v145, v253
	v_mul_f32_e32 v26, v26, v250
	v_mul_f32_e32 v27, v27, v251
	v_mul_f32_e32 v28, v28, v252
	v_mul_f32_e32 v29, v29, v253
	s_waitcnt vmcnt(22)
	v_lshlrev_b32_e32 v248, 16, v150
	v_and_b32_e32 v150, 0xffff0000, v150
	v_lshlrev_b32_e32 v249, 16, v151
	v_and_b32_e32 v151, 0xffff0000, v151
	v_max_f32_e32 v248, 0xda24260, v248
	v_max_f32_e32 v150, 0xda24260, v150
	v_max_f32_e32 v249, 0xda24260, v249
	v_max_f32_e32 v151, 0xda24260, v151
	v_rcp_f32_e32 v250, v248
	v_rcp_f32_e32 v251, v150
	v_rcp_f32_e32 v252, v249
	v_rcp_f32_e32 v253, v151
	v_fma_f32 v248, -v248, v250, 1.0
	v_fma_f32 v150, -v150, v251, 1.0
	v_fma_f32 v249, -v249, v252, 1.0
	v_fma_f32 v151, -v151, v253, 1.0
	v_fmac_f32_e32 v250, v248, v250
	v_fmac_f32_e32 v251, v150, v251
	v_fmac_f32_e32 v252, v249, v252
	v_fmac_f32_e32 v253, v151, v253
	v_lshlrev_b32_e32 v248, 16, v148
	v_and_b32_e32 v148, 0xffff0000, v148
	v_lshlrev_b32_e32 v249, 16, v149
	v_and_b32_e32 v149, 0xffff0000, v149
	v_mul_f32_e32 v250, v248, v250
	v_mul_f32_e32 v251, v148, v251
	v_mul_f32_e32 v252, v249, v252
	v_mul_f32_e32 v253, v149, v253
	v_mul_f32_e32 v54, v54, v250
	v_mul_f32_e32 v55, v55, v251
	v_mul_f32_e32 v56, v56, v252
	v_mul_f32_e32 v57, v57, v253
	s_waitcnt vmcnt(20)
	v_lshlrev_b32_e32 v248, 16, v154
	v_and_b32_e32 v154, 0xffff0000, v154
	v_lshlrev_b32_e32 v249, 16, v155
	v_and_b32_e32 v155, 0xffff0000, v155
	v_max_f32_e32 v248, 0xda24260, v248
	v_max_f32_e32 v154, 0xda24260, v154
	v_max_f32_e32 v249, 0xda24260, v249
	v_max_f32_e32 v155, 0xda24260, v155
	v_rcp_f32_e32 v250, v248
	v_rcp_f32_e32 v251, v154
	v_rcp_f32_e32 v252, v249
	v_rcp_f32_e32 v253, v155
	v_fma_f32 v248, -v248, v250, 1.0
	v_fma_f32 v154, -v154, v251, 1.0
	v_fma_f32 v249, -v249, v252, 1.0
	v_fma_f32 v155, -v155, v253, 1.0
	v_fmac_f32_e32 v250, v248, v250
	v_fmac_f32_e32 v251, v154, v251
	v_fmac_f32_e32 v252, v249, v252
	v_fmac_f32_e32 v253, v155, v253
	v_lshlrev_b32_e32 v248, 16, v152
	v_and_b32_e32 v152, 0xffff0000, v152
	v_lshlrev_b32_e32 v249, 16, v153
	v_and_b32_e32 v153, 0xffff0000, v153
	v_mul_f32_e32 v250, v248, v250
	v_mul_f32_e32 v251, v152, v251
	v_mul_f32_e32 v252, v249, v252
	v_mul_f32_e32 v253, v153, v253
	v_mul_f32_e32 v50, v50, v250
	v_mul_f32_e32 v51, v51, v251
	v_mul_f32_e32 v52, v52, v252
	v_mul_f32_e32 v53, v53, v253
	s_waitcnt vmcnt(18)
	v_lshlrev_b32_e32 v248, 16, v158
	v_and_b32_e32 v158, 0xffff0000, v158
	v_lshlrev_b32_e32 v249, 16, v159
	v_and_b32_e32 v159, 0xffff0000, v159
	v_max_f32_e32 v248, 0xda24260, v248
	v_max_f32_e32 v158, 0xda24260, v158
	v_max_f32_e32 v249, 0xda24260, v249
	v_max_f32_e32 v159, 0xda24260, v159
	v_rcp_f32_e32 v250, v248
	v_rcp_f32_e32 v251, v158
	v_rcp_f32_e32 v252, v249
	v_rcp_f32_e32 v253, v159
	v_fma_f32 v248, -v248, v250, 1.0
	v_fma_f32 v158, -v158, v251, 1.0
	v_fma_f32 v249, -v249, v252, 1.0
	v_fma_f32 v159, -v159, v253, 1.0
	v_fmac_f32_e32 v250, v248, v250
	v_fmac_f32_e32 v251, v158, v251
	v_fmac_f32_e32 v252, v249, v252
	v_fmac_f32_e32 v253, v159, v253
	v_lshlrev_b32_e32 v248, 16, v156
	v_and_b32_e32 v156, 0xffff0000, v156
	v_lshlrev_b32_e32 v249, 16, v157
	v_and_b32_e32 v157, 0xffff0000, v157
	v_mul_f32_e32 v250, v248, v250
	v_mul_f32_e32 v251, v156, v251
	v_mul_f32_e32 v252, v249, v252
	v_mul_f32_e32 v253, v157, v253
	v_mul_f32_e32 v22, v22, v250
	v_mul_f32_e32 v23, v23, v251
	v_mul_f32_e32 v24, v24, v252
	v_mul_f32_e32 v25, v25, v253
	s_waitcnt vmcnt(16)
	v_lshlrev_b32_e32 v248, 16, v162
	v_and_b32_e32 v162, 0xffff0000, v162
	v_lshlrev_b32_e32 v249, 16, v163
	v_and_b32_e32 v163, 0xffff0000, v163
	v_max_f32_e32 v248, 0xda24260, v248
	v_max_f32_e32 v162, 0xda24260, v162
	v_max_f32_e32 v249, 0xda24260, v249
	v_max_f32_e32 v163, 0xda24260, v163
	v_rcp_f32_e32 v250, v248
	v_rcp_f32_e32 v251, v162
	v_rcp_f32_e32 v252, v249
	v_rcp_f32_e32 v253, v163
	v_fma_f32 v248, -v248, v250, 1.0
	v_fma_f32 v162, -v162, v251, 1.0
	v_fma_f32 v249, -v249, v252, 1.0
	v_fma_f32 v163, -v163, v253, 1.0
	v_fmac_f32_e32 v250, v248, v250
	v_fmac_f32_e32 v251, v162, v251
	v_fmac_f32_e32 v252, v249, v252
	v_fmac_f32_e32 v253, v163, v253
	v_lshlrev_b32_e32 v248, 16, v160
	v_and_b32_e32 v160, 0xffff0000, v160
	v_lshlrev_b32_e32 v249, 16, v161
	v_and_b32_e32 v161, 0xffff0000, v161
	v_mul_f32_e32 v250, v248, v250
	v_mul_f32_e32 v251, v160, v251
	v_mul_f32_e32 v252, v249, v252
	v_mul_f32_e32 v253, v161, v253
	v_mul_f32_e32 v18, v18, v250
	v_mul_f32_e32 v19, v19, v251
	v_mul_f32_e32 v20, v20, v252
	v_mul_f32_e32 v21, v21, v253
	s_waitcnt vmcnt(14)
	v_lshlrev_b32_e32 v248, 16, v166
	v_and_b32_e32 v166, 0xffff0000, v166
	v_lshlrev_b32_e32 v249, 16, v167
	v_and_b32_e32 v167, 0xffff0000, v167
	v_max_f32_e32 v248, 0xda24260, v248
	v_max_f32_e32 v166, 0xda24260, v166
	v_max_f32_e32 v249, 0xda24260, v249
	v_max_f32_e32 v167, 0xda24260, v167
	v_rcp_f32_e32 v250, v248
	v_rcp_f32_e32 v251, v166
	v_rcp_f32_e32 v252, v249
	v_rcp_f32_e32 v253, v167
	v_fma_f32 v248, -v248, v250, 1.0
	v_fma_f32 v166, -v166, v251, 1.0
	v_fma_f32 v249, -v249, v252, 1.0
	v_fma_f32 v167, -v167, v253, 1.0
	v_fmac_f32_e32 v250, v248, v250
	v_fmac_f32_e32 v251, v166, v251
	v_fmac_f32_e32 v252, v249, v252
	v_fmac_f32_e32 v253, v167, v253
	v_lshlrev_b32_e32 v248, 16, v164
	v_and_b32_e32 v164, 0xffff0000, v164
	v_lshlrev_b32_e32 v249, 16, v165
	v_and_b32_e32 v165, 0xffff0000, v165
	v_mul_f32_e32 v250, v248, v250
	v_mul_f32_e32 v251, v164, v251
	v_mul_f32_e32 v252, v249, v252
	v_mul_f32_e32 v253, v165, v253
	v_mul_f32_e32 v46, v46, v250
	v_mul_f32_e32 v47, v47, v251
	v_mul_f32_e32 v48, v48, v252
	v_mul_f32_e32 v49, v49, v253
	s_waitcnt vmcnt(12)
	v_lshlrev_b32_e32 v248, 16, v170
	v_and_b32_e32 v170, 0xffff0000, v170
	v_lshlrev_b32_e32 v249, 16, v171
	v_and_b32_e32 v171, 0xffff0000, v171
	v_max_f32_e32 v248, 0xda24260, v248
	v_max_f32_e32 v170, 0xda24260, v170
	v_max_f32_e32 v249, 0xda24260, v249
	v_max_f32_e32 v171, 0xda24260, v171
	v_rcp_f32_e32 v250, v248
	v_rcp_f32_e32 v251, v170
	v_rcp_f32_e32 v252, v249
	v_rcp_f32_e32 v253, v171
	v_fma_f32 v248, -v248, v250, 1.0
	v_fma_f32 v170, -v170, v251, 1.0
	v_fma_f32 v249, -v249, v252, 1.0
	v_fma_f32 v171, -v171, v253, 1.0
	v_fmac_f32_e32 v250, v248, v250
	v_fmac_f32_e32 v251, v170, v251
	v_fmac_f32_e32 v252, v249, v252
	v_fmac_f32_e32 v253, v171, v253
	v_lshlrev_b32_e32 v248, 16, v168
	v_and_b32_e32 v168, 0xffff0000, v168
	v_lshlrev_b32_e32 v249, 16, v169
	v_and_b32_e32 v169, 0xffff0000, v169
	v_mul_f32_e32 v250, v248, v250
	v_mul_f32_e32 v251, v168, v251
	v_mul_f32_e32 v252, v249, v252
	v_mul_f32_e32 v253, v169, v253
	v_mul_f32_e32 v42, v42, v250
	v_mul_f32_e32 v43, v43, v251
	v_mul_f32_e32 v44, v44, v252
	v_mul_f32_e32 v45, v45, v253
	s_waitcnt vmcnt(10)
	v_lshlrev_b32_e32 v248, 16, v174
	v_and_b32_e32 v174, 0xffff0000, v174
	v_lshlrev_b32_e32 v249, 16, v175
	v_and_b32_e32 v175, 0xffff0000, v175
	v_max_f32_e32 v248, 0xda24260, v248
	v_max_f32_e32 v174, 0xda24260, v174
	v_max_f32_e32 v249, 0xda24260, v249
	v_max_f32_e32 v175, 0xda24260, v175
	v_rcp_f32_e32 v250, v248
	v_rcp_f32_e32 v251, v174
	v_rcp_f32_e32 v252, v249
	v_rcp_f32_e32 v253, v175
	v_fma_f32 v248, -v248, v250, 1.0
	v_fma_f32 v174, -v174, v251, 1.0
	v_fma_f32 v249, -v249, v252, 1.0
	v_fma_f32 v175, -v175, v253, 1.0
	v_fmac_f32_e32 v250, v248, v250
	v_fmac_f32_e32 v251, v174, v251
	v_fmac_f32_e32 v252, v249, v252
	v_fmac_f32_e32 v253, v175, v253
	v_lshlrev_b32_e32 v248, 16, v172
	v_and_b32_e32 v172, 0xffff0000, v172
	v_lshlrev_b32_e32 v249, 16, v173
	v_and_b32_e32 v173, 0xffff0000, v173
	v_mul_f32_e32 v250, v248, v250
	v_mul_f32_e32 v251, v172, v251
	v_mul_f32_e32 v252, v249, v252
	v_mul_f32_e32 v253, v173, v253
	v_mul_f32_e32 v14, v14, v250
	v_mul_f32_e32 v15, v15, v251
	v_mul_f32_e32 v16, v16, v252
	v_mul_f32_e32 v17, v17, v253
	s_waitcnt vmcnt(8)
	v_lshlrev_b32_e32 v248, 16, v178
	v_and_b32_e32 v178, 0xffff0000, v178
	v_lshlrev_b32_e32 v249, 16, v179
	v_and_b32_e32 v179, 0xffff0000, v179
	v_max_f32_e32 v248, 0xda24260, v248
	v_max_f32_e32 v178, 0xda24260, v178
	v_max_f32_e32 v249, 0xda24260, v249
	v_max_f32_e32 v179, 0xda24260, v179
	v_rcp_f32_e32 v250, v248
	v_rcp_f32_e32 v251, v178
	v_rcp_f32_e32 v252, v249
	v_rcp_f32_e32 v253, v179
	v_fma_f32 v248, -v248, v250, 1.0
	v_fma_f32 v178, -v178, v251, 1.0
	v_fma_f32 v249, -v249, v252, 1.0
	v_fma_f32 v179, -v179, v253, 1.0
	v_fmac_f32_e32 v250, v248, v250
	v_fmac_f32_e32 v251, v178, v251
	v_fmac_f32_e32 v252, v249, v252
	v_fmac_f32_e32 v253, v179, v253
	v_lshlrev_b32_e32 v248, 16, v176
	v_and_b32_e32 v176, 0xffff0000, v176
	v_lshlrev_b32_e32 v249, 16, v177
	v_and_b32_e32 v177, 0xffff0000, v177
	v_mul_f32_e32 v250, v248, v250
	v_mul_f32_e32 v251, v176, v251
	v_mul_f32_e32 v252, v249, v252
	v_mul_f32_e32 v253, v177, v253
	v_mul_f32_e32 v10, v10, v250
	v_mul_f32_e32 v11, v11, v251
	v_mul_f32_e32 v12, v12, v252
	v_mul_f32_e32 v13, v13, v253
	s_waitcnt vmcnt(6)
	v_lshlrev_b32_e32 v248, 16, v182
	v_and_b32_e32 v182, 0xffff0000, v182
	v_lshlrev_b32_e32 v249, 16, v183
	v_and_b32_e32 v183, 0xffff0000, v183
	v_max_f32_e32 v248, 0xda24260, v248
	v_max_f32_e32 v182, 0xda24260, v182
	v_max_f32_e32 v249, 0xda24260, v249
	v_max_f32_e32 v183, 0xda24260, v183
	v_rcp_f32_e32 v250, v248
	v_rcp_f32_e32 v251, v182
	v_rcp_f32_e32 v252, v249
	v_rcp_f32_e32 v253, v183
	v_fma_f32 v248, -v248, v250, 1.0
	v_fma_f32 v182, -v182, v251, 1.0
	v_fma_f32 v249, -v249, v252, 1.0
	v_fma_f32 v183, -v183, v253, 1.0
	v_fmac_f32_e32 v250, v248, v250
	v_fmac_f32_e32 v251, v182, v251
	v_fmac_f32_e32 v252, v249, v252
	v_fmac_f32_e32 v253, v183, v253
	v_lshlrev_b32_e32 v248, 16, v180
	v_and_b32_e32 v180, 0xffff0000, v180
	v_lshlrev_b32_e32 v249, 16, v181
	v_and_b32_e32 v181, 0xffff0000, v181
	v_mul_f32_e32 v250, v248, v250
	v_mul_f32_e32 v251, v180, v251
	v_mul_f32_e32 v252, v249, v252
	v_mul_f32_e32 v253, v181, v253
	v_mul_f32_e32 v38, v38, v250
	v_mul_f32_e32 v39, v39, v251
	v_mul_f32_e32 v40, v40, v252
	v_mul_f32_e32 v41, v41, v253
	s_waitcnt vmcnt(4)
	v_lshlrev_b32_e32 v248, 16, v186
	v_and_b32_e32 v186, 0xffff0000, v186
	v_lshlrev_b32_e32 v249, 16, v187
	v_and_b32_e32 v187, 0xffff0000, v187
	v_max_f32_e32 v248, 0xda24260, v248
	v_max_f32_e32 v186, 0xda24260, v186
	v_max_f32_e32 v249, 0xda24260, v249
	v_max_f32_e32 v187, 0xda24260, v187
	v_rcp_f32_e32 v250, v248
	v_rcp_f32_e32 v251, v186
	v_rcp_f32_e32 v252, v249
	v_rcp_f32_e32 v253, v187
	v_fma_f32 v248, -v248, v250, 1.0
	v_fma_f32 v186, -v186, v251, 1.0
	v_fma_f32 v249, -v249, v252, 1.0
	v_fma_f32 v187, -v187, v253, 1.0
	v_fmac_f32_e32 v250, v248, v250
	v_fmac_f32_e32 v251, v186, v251
	v_fmac_f32_e32 v252, v249, v252
	v_fmac_f32_e32 v253, v187, v253
	v_lshlrev_b32_e32 v248, 16, v184
	v_and_b32_e32 v184, 0xffff0000, v184
	v_lshlrev_b32_e32 v249, 16, v185
	v_and_b32_e32 v185, 0xffff0000, v185
	v_mul_f32_e32 v250, v248, v250
	v_mul_f32_e32 v251, v184, v251
	v_mul_f32_e32 v252, v249, v252
	v_mul_f32_e32 v253, v185, v253
	v_mul_f32_e32 v34, v34, v250
	v_mul_f32_e32 v35, v35, v251
	v_mul_f32_e32 v36, v36, v252
	v_mul_f32_e32 v37, v37, v253
	s_waitcnt vmcnt(2)
	v_lshlrev_b32_e32 v248, 16, v198
	v_and_b32_e32 v198, 0xffff0000, v198
	v_lshlrev_b32_e32 v249, 16, v199
	v_and_b32_e32 v199, 0xffff0000, v199
	v_max_f32_e32 v248, 0xda24260, v248
	v_max_f32_e32 v198, 0xda24260, v198
	v_max_f32_e32 v249, 0xda24260, v249
	v_max_f32_e32 v199, 0xda24260, v199
	v_rcp_f32_e32 v250, v248
	v_rcp_f32_e32 v251, v198
	v_rcp_f32_e32 v252, v249
	v_rcp_f32_e32 v253, v199
	v_fma_f32 v248, -v248, v250, 1.0
	v_fma_f32 v198, -v198, v251, 1.0
	v_fma_f32 v249, -v249, v252, 1.0
	v_fma_f32 v199, -v199, v253, 1.0
	v_fmac_f32_e32 v250, v248, v250
	v_fmac_f32_e32 v251, v198, v251
	v_fmac_f32_e32 v252, v249, v252
	v_fmac_f32_e32 v253, v199, v253
	v_lshlrev_b32_e32 v248, 16, v188
	v_and_b32_e32 v188, 0xffff0000, v188
	v_lshlrev_b32_e32 v249, 16, v189
	v_and_b32_e32 v189, 0xffff0000, v189
	v_mul_f32_e32 v250, v248, v250
	v_mul_f32_e32 v251, v188, v251
	v_mul_f32_e32 v252, v249, v252
	v_mul_f32_e32 v253, v189, v253
	v_mul_f32_e32 v6, v6, v250
	v_mul_f32_e32 v7, v7, v251
	v_mul_f32_e32 v8, v8, v252
	v_mul_f32_e32 v9, v9, v253
	s_waitcnt vmcnt(0)
	v_lshlrev_b32_e32 v248, 16, v202
	v_and_b32_e32 v202, 0xffff0000, v202
	v_lshlrev_b32_e32 v249, 16, v203
	v_and_b32_e32 v203, 0xffff0000, v203
	v_max_f32_e32 v248, 0xda24260, v248
	v_max_f32_e32 v202, 0xda24260, v202
	v_max_f32_e32 v249, 0xda24260, v249
	v_max_f32_e32 v203, 0xda24260, v203
	v_rcp_f32_e32 v250, v248
	v_rcp_f32_e32 v251, v202
	v_rcp_f32_e32 v252, v249
	v_rcp_f32_e32 v253, v203
	v_fma_f32 v248, -v248, v250, 1.0
	v_fma_f32 v202, -v202, v251, 1.0
	v_fma_f32 v249, -v249, v252, 1.0
	v_fma_f32 v203, -v203, v253, 1.0
	v_fmac_f32_e32 v250, v248, v250
	v_fmac_f32_e32 v251, v202, v251
	v_fmac_f32_e32 v252, v249, v252
	v_fmac_f32_e32 v253, v203, v253
	v_lshlrev_b32_e32 v248, 16, v200
	v_and_b32_e32 v200, 0xffff0000, v200
	v_lshlrev_b32_e32 v249, 16, v201
	v_and_b32_e32 v201, 0xffff0000, v201
	v_mul_f32_e32 v250, v248, v250
	v_mul_f32_e32 v251, v200, v251
	v_mul_f32_e32 v252, v249, v252
	v_mul_f32_e32 v253, v201, v253
	v_mul_f32_e32 v2, v2, v250
	v_mul_f32_e32 v3, v3, v251
	v_mul_f32_e32 v4, v4, v252
	v_mul_f32_e32 v5, v5, v253
	s_branch .LBB0_254
